# in-proj epilogue gate columns: packed mul/add and SDWA byte-preserve packing (36 instead of 52 VALU per 8 gates), same arithmetic
# speedup vs baseline: 1.0113x; 1.0113x over previous
; __device__ __forceinline__ float sigmoidf_(float x) { return __builtin_amdgcn_rcpf(1.f + __expf(-x)); }
;     __device__ __forceinline__ void operator()(f32x4 (&acc)[2][2][4][2], const pg8::Unit& u, int wr, int wc, int fr, int fq) const {
;     ...
;         if (u.pn >= 28) {
; #pragma unroll
;             for (int ai = 0; ai < 2; ++ai)
; #pragma unroll
;                 for (int m = 0; m < 4; ++m) {
;                     unsigned char* gp = gq + (size_t)(row0 + ai * 128 + m * 16) * 4096 + (u.pn - 28) * 256 + cin;
; #pragma unroll
;                     for (int bj = 0; bj < 2; ++bj) { unsigned w2[2];
; #pragma unroll
;                         for (int n = 0; n < 2; ++n) {
;                             const f32x4 v = acc[ai][bj][m][n];
;                             const unsigned b0 = (unsigned)(sigmoidf_(v[0]) * 255.f + 0.5f), b1 = (unsigned)(sigmoidf_(v[1]) * 255.f + 0.5f),
;                                            b2 = (unsigned)(sigmoidf_(v[2]) * 255.f + 0.5f), b3 = (unsigned)(sigmoidf_(v[3]) * 255.f + 0.5f);
;                             w2[n] = b0 | (b1 << 8) | (b2 << 16) | (b3 << 24);
;                         }
;                         u32x2 o = {w2[0], w2[1]}; *(u32x2*)(gp + bj * 128) = o; }
.LBB0_1065:
	s_and_b64 vcc, exec, s[0:1]
	s_cbranch_vccz .LBB0_1067
	v_readlane_b32 s52, v251, 1
	v_readlane_b32 s53, v251, 2
	v_readlane_b32 s54, v251, 3
	v_readlane_b32 s55, v251, 4
	v_readlane_b32 s56, v251, 5
	v_readlane_b32 s57, v251, 6
	v_readlane_b32 s58, v251, 7
	v_readlane_b32 s59, v251, 8
	v_ashrrev_i32_e32 v155, 31, v154
	s_add_i32 s0, s22, 0xffffe400
	v_lshlrev_b64 v[192:193], 12, v[154:155]
	s_ashr_i32 s1, s0, 31
	v_lshl_add_u64 v[192:193], s[58:59], 0, v[192:193]
	s_mov_b32 s20, 0x437f0000
	s_mov_b32 s21, 0xbfb8aa3b
	v_lshl_add_u64 v[192:193], v[192:193], 0, s[0:1]
	v_lshl_add_u64 v[192:193], v[192:193], 0, v[142:143]
	v_pk_mul_f32 v[172:173], v[126:127], s[20:21] op_sel:[0,1] op_sel_hi:[1,1]
	v_pk_mul_f32 v[174:175], v[128:129], s[20:21] op_sel:[0,1] op_sel_hi:[1,1]
	v_pk_mul_f32 v[176:177], v[122:123], s[20:21] op_sel:[0,1] op_sel_hi:[1,1]
	v_pk_mul_f32 v[178:179], v[124:125], s[20:21] op_sel:[0,1] op_sel_hi:[1,1]
	v_exp_f32_e32 v172, v172
	v_exp_f32_e32 v173, v173
	v_exp_f32_e32 v174, v174
	v_exp_f32_e32 v175, v175
	v_exp_f32_e32 v176, v176
	v_exp_f32_e32 v177, v177
	v_exp_f32_e32 v178, v178
	v_exp_f32_e32 v179, v179
	v_pk_add_f32 v[172:173], v[172:173], 1.0 op_sel_hi:[1,0]
	v_pk_add_f32 v[174:175], v[174:175], 1.0 op_sel_hi:[1,0]
	v_pk_add_f32 v[176:177], v[176:177], 1.0 op_sel_hi:[1,0]
	v_pk_add_f32 v[178:179], v[178:179], 1.0 op_sel_hi:[1,0]
	v_rcp_f32_e32 v172, v172
	v_rcp_f32_e32 v173, v173
	v_rcp_f32_e32 v174, v174
	v_rcp_f32_e32 v175, v175
	v_rcp_f32_e32 v176, v176
	v_rcp_f32_e32 v177, v177
	v_rcp_f32_e32 v178, v178
	v_rcp_f32_e32 v179, v179
	s_nop 0
	v_pk_fma_f32 v[172:173], v[172:173], s[20:21], 0.5 op_sel_hi:[1,0,0]
	v_pk_fma_f32 v[174:175], v[174:175], s[20:21], 0.5 op_sel_hi:[1,0,0]
	v_pk_fma_f32 v[176:177], v[176:177], s[20:21], 0.5 op_sel_hi:[1,0,0]
	v_pk_fma_f32 v[178:179], v[178:179], s[20:21], 0.5 op_sel_hi:[1,0,0]
	v_cvt_u32_f32_e32 v180, v172
	v_cvt_u32_f32_e32 v181, v176
	v_cvt_u32_f32_sdwa v180, v173 dst_sel:BYTE_1 dst_unused:UNUSED_PRESERVE src0_sel:DWORD
	v_cvt_u32_f32_sdwa v181, v177 dst_sel:BYTE_1 dst_unused:UNUSED_PRESERVE src0_sel:DWORD
	v_cvt_u32_f32_sdwa v180, v174 dst_sel:BYTE_2 dst_unused:UNUSED_PRESERVE src0_sel:DWORD
	v_cvt_u32_f32_sdwa v181, v178 dst_sel:BYTE_2 dst_unused:UNUSED_PRESERVE src0_sel:DWORD
	v_cvt_u32_f32_sdwa v180, v175 dst_sel:BYTE_3 dst_unused:UNUSED_PRESERVE src0_sel:DWORD
	v_cvt_u32_f32_sdwa v181, v179 dst_sel:BYTE_3 dst_unused:UNUSED_PRESERVE src0_sel:DWORD
	global_store_dwordx2 v[192:193], v[180:181], off
	v_pk_mul_f32 v[182:183], v[118:119], s[20:21] op_sel:[0,1] op_sel_hi:[1,1]
	v_pk_mul_f32 v[184:185], v[120:121], s[20:21] op_sel:[0,1] op_sel_hi:[1,1]
	v_pk_mul_f32 v[186:187], v[110:111], s[20:21] op_sel:[0,1] op_sel_hi:[1,1]
	v_pk_mul_f32 v[188:189], v[112:113], s[20:21] op_sel:[0,1] op_sel_hi:[1,1]
	v_exp_f32_e32 v182, v182
	v_exp_f32_e32 v183, v183
	v_exp_f32_e32 v184, v184
	v_exp_f32_e32 v185, v185
	v_exp_f32_e32 v186, v186
	v_exp_f32_e32 v187, v187
	v_exp_f32_e32 v188, v188
	v_exp_f32_e32 v189, v189
	v_pk_add_f32 v[182:183], v[182:183], 1.0 op_sel_hi:[1,0]
	v_pk_add_f32 v[184:185], v[184:185], 1.0 op_sel_hi:[1,0]
	v_pk_add_f32 v[186:187], v[186:187], 1.0 op_sel_hi:[1,0]
	v_pk_add_f32 v[188:189], v[188:189], 1.0 op_sel_hi:[1,0]
	v_rcp_f32_e32 v182, v182
	v_rcp_f32_e32 v183, v183
	v_rcp_f32_e32 v184, v184
	v_rcp_f32_e32 v185, v185
	v_rcp_f32_e32 v186, v186
	v_rcp_f32_e32 v187, v187
	v_rcp_f32_e32 v188, v188
	v_rcp_f32_e32 v189, v189
	s_nop 0
	v_pk_fma_f32 v[182:183], v[182:183], s[20:21], 0.5 op_sel_hi:[1,0,0]
	v_pk_fma_f32 v[184:185], v[184:185], s[20:21], 0.5 op_sel_hi:[1,0,0]
	v_pk_fma_f32 v[186:187], v[186:187], s[20:21], 0.5 op_sel_hi:[1,0,0]
	v_pk_fma_f32 v[188:189], v[188:189], s[20:21], 0.5 op_sel_hi:[1,0,0]
	v_cvt_u32_f32_e32 v190, v182
	v_cvt_u32_f32_e32 v191, v186
	v_cvt_u32_f32_sdwa v190, v183 dst_sel:BYTE_1 dst_unused:UNUSED_PRESERVE src0_sel:DWORD
	v_cvt_u32_f32_sdwa v191, v187 dst_sel:BYTE_1 dst_unused:UNUSED_PRESERVE src0_sel:DWORD
	v_cvt_u32_f32_sdwa v190, v184 dst_sel:BYTE_2 dst_unused:UNUSED_PRESERVE src0_sel:DWORD
	v_cvt_u32_f32_sdwa v191, v188 dst_sel:BYTE_2 dst_unused:UNUSED_PRESERVE src0_sel:DWORD
	v_cvt_u32_f32_sdwa v190, v185 dst_sel:BYTE_3 dst_unused:UNUSED_PRESERVE src0_sel:DWORD
	v_cvt_u32_f32_sdwa v191, v189 dst_sel:BYTE_3 dst_unused:UNUSED_PRESERVE src0_sel:DWORD
	global_store_dwordx2 v[192:193], v[190:191], off offset:128
	v_pk_mul_f32 v[172:173], v[114:115], s[20:21] op_sel:[0,1] op_sel_hi:[1,1]
	v_pk_mul_f32 v[174:175], v[116:117], s[20:21] op_sel:[0,1] op_sel_hi:[1,1]
	v_pk_mul_f32 v[176:177], v[106:107], s[20:21] op_sel:[0,1] op_sel_hi:[1,1]
	v_pk_mul_f32 v[178:179], v[108:109], s[20:21] op_sel:[0,1] op_sel_hi:[1,1]
	v_exp_f32_e32 v172, v172
	v_exp_f32_e32 v173, v173
	v_exp_f32_e32 v174, v174
	v_exp_f32_e32 v175, v175
	v_exp_f32_e32 v176, v176
	v_exp_f32_e32 v177, v177
	v_exp_f32_e32 v178, v178
	v_exp_f32_e32 v179, v179
	v_pk_add_f32 v[172:173], v[172:173], 1.0 op_sel_hi:[1,0]
	v_pk_add_f32 v[174:175], v[174:175], 1.0 op_sel_hi:[1,0]
	v_pk_add_f32 v[176:177], v[176:177], 1.0 op_sel_hi:[1,0]
	v_pk_add_f32 v[178:179], v[178:179], 1.0 op_sel_hi:[1,0]
	v_rcp_f32_e32 v172, v172
	v_rcp_f32_e32 v173, v173
	v_rcp_f32_e32 v174, v174
	v_rcp_f32_e32 v175, v175
	v_rcp_f32_e32 v176, v176
	v_rcp_f32_e32 v177, v177
	v_rcp_f32_e32 v178, v178
	v_rcp_f32_e32 v179, v179
	s_mov_b64 s[0:1], 0x10000
	v_lshl_add_u64 v[196:197], v[192:193], 0, s[0:1]
	v_pk_fma_f32 v[172:173], v[172:173], s[20:21], 0.5 op_sel_hi:[1,0,0]
	v_pk_fma_f32 v[174:175], v[174:175], s[20:21], 0.5 op_sel_hi:[1,0,0]
	v_pk_fma_f32 v[176:177], v[176:177], s[20:21], 0.5 op_sel_hi:[1,0,0]
; __device__ __forceinline__ float sigmoidf_(float x) { return __builtin_amdgcn_rcpf(1.f + __expf(-x)); }
;     __device__ __forceinline__ void operator()(f32x4 (&acc)[2][2][4][2], const pg8::Unit& u, int wr, int wc, int fr, int fq) const {
;     ...
;             for (int ai = 0; ai < 2; ++ai)
; #pragma unroll
;                 for (int m = 0; m < 4; ++m) {
;                     unsigned char* gp = gq + (size_t)(row0 + ai * 128 + m * 16) * 4096 + (u.pn - 28) * 256 + cin;
; #pragma unroll
;                     for (int bj = 0; bj < 2; ++bj) { unsigned w2[2];
; #pragma unroll
;                         for (int n = 0; n < 2; ++n) {
;                             const f32x4 v = acc[ai][bj][m][n];
;                             const unsigned b0 = (unsigned)(sigmoidf_(v[0]) * 255.f + 0.5f), b1 = (unsigned)(sigmoidf_(v[1]) * 255.f + 0.5f),
;                                            b2 = (unsigned)(sigmoidf_(v[2]) * 255.f + 0.5f), b3 = (unsigned)(sigmoidf_(v[3]) * 255.f + 0.5f);
;                             w2[n] = b0 | (b1 << 8) | (b2 << 16) | (b3 << 24);
;                         }
;                         u32x2 o = {w2[0], w2[1]}; *(u32x2*)(gp + bj * 128) = o; }
	v_pk_fma_f32 v[178:179], v[178:179], s[20:21], 0.5 op_sel_hi:[1,0,0]
	v_cvt_u32_f32_e32 v180, v172
	v_cvt_u32_f32_e32 v181, v176
	v_cvt_u32_f32_sdwa v180, v173 dst_sel:BYTE_1 dst_unused:UNUSED_PRESERVE src0_sel:DWORD
	v_cvt_u32_f32_sdwa v181, v177 dst_sel:BYTE_1 dst_unused:UNUSED_PRESERVE src0_sel:DWORD
	v_cvt_u32_f32_sdwa v180, v174 dst_sel:BYTE_2 dst_unused:UNUSED_PRESERVE src0_sel:DWORD
	v_cvt_u32_f32_sdwa v181, v178 dst_sel:BYTE_2 dst_unused:UNUSED_PRESERVE src0_sel:DWORD
	v_cvt_u32_f32_sdwa v180, v175 dst_sel:BYTE_3 dst_unused:UNUSED_PRESERVE src0_sel:DWORD
	v_cvt_u32_f32_sdwa v181, v179 dst_sel:BYTE_3 dst_unused:UNUSED_PRESERVE src0_sel:DWORD
	global_store_dwordx2 v[196:197], v[180:181], off
	v_pk_mul_f32 v[182:183], v[98:99], s[20:21] op_sel:[0,1] op_sel_hi:[1,1]
	v_pk_mul_f32 v[184:185], v[100:101], s[20:21] op_sel:[0,1] op_sel_hi:[1,1]
	v_pk_mul_f32 v[186:187], v[90:91], s[20:21] op_sel:[0,1] op_sel_hi:[1,1]
	v_pk_mul_f32 v[188:189], v[92:93], s[20:21] op_sel:[0,1] op_sel_hi:[1,1]
	v_exp_f32_e32 v182, v182
	v_exp_f32_e32 v183, v183
	v_exp_f32_e32 v184, v184
	v_exp_f32_e32 v185, v185
	v_exp_f32_e32 v186, v186
	v_exp_f32_e32 v187, v187
	v_exp_f32_e32 v188, v188
	v_exp_f32_e32 v189, v189
	v_pk_add_f32 v[182:183], v[182:183], 1.0 op_sel_hi:[1,0]
	v_pk_add_f32 v[184:185], v[184:185], 1.0 op_sel_hi:[1,0]
	v_pk_add_f32 v[186:187], v[186:187], 1.0 op_sel_hi:[1,0]
	v_pk_add_f32 v[188:189], v[188:189], 1.0 op_sel_hi:[1,0]
	v_rcp_f32_e32 v182, v182
	v_rcp_f32_e32 v183, v183
	v_rcp_f32_e32 v184, v184
	v_rcp_f32_e32 v185, v185
	v_rcp_f32_e32 v186, v186
	v_rcp_f32_e32 v187, v187
	v_rcp_f32_e32 v188, v188
	v_rcp_f32_e32 v189, v189
	s_nop 0
	v_pk_fma_f32 v[182:183], v[182:183], s[20:21], 0.5 op_sel_hi:[1,0,0]
	v_pk_fma_f32 v[184:185], v[184:185], s[20:21], 0.5 op_sel_hi:[1,0,0]
	v_pk_fma_f32 v[186:187], v[186:187], s[20:21], 0.5 op_sel_hi:[1,0,0]
	v_pk_fma_f32 v[188:189], v[188:189], s[20:21], 0.5 op_sel_hi:[1,0,0]
	v_cvt_u32_f32_e32 v190, v182
	v_cvt_u32_f32_e32 v191, v186
	v_cvt_u32_f32_sdwa v190, v183 dst_sel:BYTE_1 dst_unused:UNUSED_PRESERVE src0_sel:DWORD
	v_cvt_u32_f32_sdwa v191, v187 dst_sel:BYTE_1 dst_unused:UNUSED_PRESERVE src0_sel:DWORD
	v_cvt_u32_f32_sdwa v190, v184 dst_sel:BYTE_2 dst_unused:UNUSED_PRESERVE src0_sel:DWORD
	v_cvt_u32_f32_sdwa v191, v188 dst_sel:BYTE_2 dst_unused:UNUSED_PRESERVE src0_sel:DWORD
	v_cvt_u32_f32_sdwa v190, v185 dst_sel:BYTE_3 dst_unused:UNUSED_PRESERVE src0_sel:DWORD
	v_cvt_u32_f32_sdwa v191, v189 dst_sel:BYTE_3 dst_unused:UNUSED_PRESERVE src0_sel:DWORD
	global_store_dwordx2 v[196:197], v[190:191], off offset:128
	v_pk_mul_f32 v[172:173], v[102:103], s[20:21] op_sel:[0,1] op_sel_hi:[1,1]
	v_pk_mul_f32 v[174:175], v[104:105], s[20:21] op_sel:[0,1] op_sel_hi:[1,1]
	v_pk_mul_f32 v[176:177], v[94:95], s[20:21] op_sel:[0,1] op_sel_hi:[1,1]
	v_pk_mul_f32 v[178:179], v[96:97], s[20:21] op_sel:[0,1] op_sel_hi:[1,1]
	v_exp_f32_e32 v172, v172
	v_exp_f32_e32 v173, v173
	v_exp_f32_e32 v174, v174
	v_exp_f32_e32 v175, v175
	v_exp_f32_e32 v176, v176
	v_exp_f32_e32 v177, v177
	v_exp_f32_e32 v178, v178
	v_exp_f32_e32 v179, v179
	v_pk_add_f32 v[172:173], v[172:173], 1.0 op_sel_hi:[1,0]
	v_pk_add_f32 v[174:175], v[174:175], 1.0 op_sel_hi:[1,0]
	v_pk_add_f32 v[176:177], v[176:177], 1.0 op_sel_hi:[1,0]
	v_pk_add_f32 v[178:179], v[178:179], 1.0 op_sel_hi:[1,0]
	v_rcp_f32_e32 v172, v172
	v_rcp_f32_e32 v173, v173
	v_rcp_f32_e32 v174, v174
	v_rcp_f32_e32 v175, v175
	v_rcp_f32_e32 v176, v176
	v_rcp_f32_e32 v177, v177
	v_rcp_f32_e32 v178, v178
	v_rcp_f32_e32 v179, v179
	s_mov_b64 s[0:1], 0x20000
	v_lshl_add_u64 v[194:195], v[192:193], 0, s[0:1]
	v_pk_fma_f32 v[172:173], v[172:173], s[20:21], 0.5 op_sel_hi:[1,0,0]
	v_pk_fma_f32 v[174:175], v[174:175], s[20:21], 0.5 op_sel_hi:[1,0,0]
	v_pk_fma_f32 v[176:177], v[176:177], s[20:21], 0.5 op_sel_hi:[1,0,0]
	v_pk_fma_f32 v[178:179], v[178:179], s[20:21], 0.5 op_sel_hi:[1,0,0]
	v_cvt_u32_f32_e32 v180, v172
	v_cvt_u32_f32_e32 v181, v176
	v_cvt_u32_f32_sdwa v180, v173 dst_sel:BYTE_1 dst_unused:UNUSED_PRESERVE src0_sel:DWORD
	v_cvt_u32_f32_sdwa v181, v177 dst_sel:BYTE_1 dst_unused:UNUSED_PRESERVE src0_sel:DWORD
	v_cvt_u32_f32_sdwa v180, v174 dst_sel:BYTE_2 dst_unused:UNUSED_PRESERVE src0_sel:DWORD
	v_cvt_u32_f32_sdwa v181, v178 dst_sel:BYTE_2 dst_unused:UNUSED_PRESERVE src0_sel:DWORD
	v_cvt_u32_f32_sdwa v180, v175 dst_sel:BYTE_3 dst_unused:UNUSED_PRESERVE src0_sel:DWORD
	v_cvt_u32_f32_sdwa v181, v179 dst_sel:BYTE_3 dst_unused:UNUSED_PRESERVE src0_sel:DWORD
	global_store_dwordx2 v[194:195], v[180:181], off
	v_pk_mul_f32 v[182:183], v[82:83], s[20:21] op_sel:[0,1] op_sel_hi:[1,1]
	v_pk_mul_f32 v[184:185], v[84:85], s[20:21] op_sel:[0,1] op_sel_hi:[1,1]
	v_pk_mul_f32 v[186:187], v[74:75], s[20:21] op_sel:[0,1] op_sel_hi:[1,1]
	v_pk_mul_f32 v[188:189], v[76:77], s[20:21] op_sel:[0,1] op_sel_hi:[1,1]
	v_exp_f32_e32 v182, v182
	v_exp_f32_e32 v183, v183
	v_exp_f32_e32 v184, v184
	v_exp_f32_e32 v185, v185
	v_exp_f32_e32 v186, v186
	v_exp_f32_e32 v187, v187
	v_exp_f32_e32 v188, v188
	v_exp_f32_e32 v189, v189
	v_pk_add_f32 v[182:183], v[182:183], 1.0 op_sel_hi:[1,0]
	v_pk_add_f32 v[184:185], v[184:185], 1.0 op_sel_hi:[1,0]
	v_pk_add_f32 v[186:187], v[186:187], 1.0 op_sel_hi:[1,0]
	v_pk_add_f32 v[188:189], v[188:189], 1.0 op_sel_hi:[1,0]
	v_rcp_f32_e32 v182, v182
	v_rcp_f32_e32 v183, v183
	v_rcp_f32_e32 v184, v184
	v_rcp_f32_e32 v185, v185
	v_rcp_f32_e32 v186, v186
	v_rcp_f32_e32 v187, v187
	v_rcp_f32_e32 v188, v188
	v_rcp_f32_e32 v189, v189
	s_nop 0
	v_pk_fma_f32 v[182:183], v[182:183], s[20:21], 0.5 op_sel_hi:[1,0,0]
	v_pk_fma_f32 v[184:185], v[184:185], s[20:21], 0.5 op_sel_hi:[1,0,0]
; __device__ __forceinline__ float sigmoidf_(float x) { return __builtin_amdgcn_rcpf(1.f + __expf(-x)); }
;     __device__ __forceinline__ void operator()(f32x4 (&acc)[2][2][4][2], const pg8::Unit& u, int wr, int wc, int fr, int fq) const {
;     ...
;             for (int ai = 0; ai < 2; ++ai)
; #pragma unroll
;                 for (int m = 0; m < 4; ++m) {
;                     unsigned char* gp = gq + (size_t)(row0 + ai * 128 + m * 16) * 4096 + (u.pn - 28) * 256 + cin;
; #pragma unroll
;                     for (int bj = 0; bj < 2; ++bj) { unsigned w2[2];
; #pragma unroll
;                         for (int n = 0; n < 2; ++n) {
;                             const f32x4 v = acc[ai][bj][m][n];
;                             const unsigned b0 = (unsigned)(sigmoidf_(v[0]) * 255.f + 0.5f), b1 = (unsigned)(sigmoidf_(v[1]) * 255.f + 0.5f),
;                                            b2 = (unsigned)(sigmoidf_(v[2]) * 255.f + 0.5f), b3 = (unsigned)(sigmoidf_(v[3]) * 255.f + 0.5f);
;                             w2[n] = b0 | (b1 << 8) | (b2 << 16) | (b3 << 24);
;                         }
;                         u32x2 o = {w2[0], w2[1]}; *(u32x2*)(gp + bj * 128) = o; }
	v_pk_fma_f32 v[186:187], v[186:187], s[20:21], 0.5 op_sel_hi:[1,0,0]
	v_pk_fma_f32 v[188:189], v[188:189], s[20:21], 0.5 op_sel_hi:[1,0,0]
	v_cvt_u32_f32_e32 v190, v182
	v_cvt_u32_f32_e32 v191, v186
	v_cvt_u32_f32_sdwa v190, v183 dst_sel:BYTE_1 dst_unused:UNUSED_PRESERVE src0_sel:DWORD
	v_cvt_u32_f32_sdwa v191, v187 dst_sel:BYTE_1 dst_unused:UNUSED_PRESERVE src0_sel:DWORD
	v_cvt_u32_f32_sdwa v190, v184 dst_sel:BYTE_2 dst_unused:UNUSED_PRESERVE src0_sel:DWORD
	v_cvt_u32_f32_sdwa v191, v188 dst_sel:BYTE_2 dst_unused:UNUSED_PRESERVE src0_sel:DWORD
	v_cvt_u32_f32_sdwa v190, v185 dst_sel:BYTE_3 dst_unused:UNUSED_PRESERVE src0_sel:DWORD
	v_cvt_u32_f32_sdwa v191, v189 dst_sel:BYTE_3 dst_unused:UNUSED_PRESERVE src0_sel:DWORD
	global_store_dwordx2 v[194:195], v[190:191], off offset:128
	v_pk_mul_f32 v[172:173], v[86:87], s[20:21] op_sel:[0,1] op_sel_hi:[1,1]
	v_pk_mul_f32 v[174:175], v[88:89], s[20:21] op_sel:[0,1] op_sel_hi:[1,1]
	v_pk_mul_f32 v[176:177], v[78:79], s[20:21] op_sel:[0,1] op_sel_hi:[1,1]
	v_pk_mul_f32 v[178:179], v[80:81], s[20:21] op_sel:[0,1] op_sel_hi:[1,1]
	v_exp_f32_e32 v172, v172
	v_exp_f32_e32 v173, v173
	v_exp_f32_e32 v174, v174
	v_exp_f32_e32 v175, v175
	v_exp_f32_e32 v176, v176
	v_exp_f32_e32 v177, v177
	v_exp_f32_e32 v178, v178
	v_exp_f32_e32 v179, v179
	v_pk_add_f32 v[172:173], v[172:173], 1.0 op_sel_hi:[1,0]
	v_pk_add_f32 v[174:175], v[174:175], 1.0 op_sel_hi:[1,0]
	v_pk_add_f32 v[176:177], v[176:177], 1.0 op_sel_hi:[1,0]
	v_pk_add_f32 v[178:179], v[178:179], 1.0 op_sel_hi:[1,0]
	v_rcp_f32_e32 v172, v172
	v_rcp_f32_e32 v173, v173
	v_rcp_f32_e32 v174, v174
	v_rcp_f32_e32 v175, v175
	v_rcp_f32_e32 v176, v176
	v_rcp_f32_e32 v177, v177
	v_rcp_f32_e32 v178, v178
	v_rcp_f32_e32 v179, v179
	s_mov_b64 s[0:1], 0x30000
	v_lshl_add_u64 v[196:197], v[192:193], 0, s[0:1]
	v_pk_fma_f32 v[172:173], v[172:173], s[20:21], 0.5 op_sel_hi:[1,0,0]
	v_pk_fma_f32 v[174:175], v[174:175], s[20:21], 0.5 op_sel_hi:[1,0,0]
	v_pk_fma_f32 v[176:177], v[176:177], s[20:21], 0.5 op_sel_hi:[1,0,0]
	v_pk_fma_f32 v[178:179], v[178:179], s[20:21], 0.5 op_sel_hi:[1,0,0]
	v_cvt_u32_f32_e32 v180, v172
	v_cvt_u32_f32_e32 v181, v176
	v_cvt_u32_f32_sdwa v180, v173 dst_sel:BYTE_1 dst_unused:UNUSED_PRESERVE src0_sel:DWORD
	v_cvt_u32_f32_sdwa v181, v177 dst_sel:BYTE_1 dst_unused:UNUSED_PRESERVE src0_sel:DWORD
	v_cvt_u32_f32_sdwa v180, v174 dst_sel:BYTE_2 dst_unused:UNUSED_PRESERVE src0_sel:DWORD
	v_cvt_u32_f32_sdwa v181, v178 dst_sel:BYTE_2 dst_unused:UNUSED_PRESERVE src0_sel:DWORD
	v_cvt_u32_f32_sdwa v180, v175 dst_sel:BYTE_3 dst_unused:UNUSED_PRESERVE src0_sel:DWORD
	v_cvt_u32_f32_sdwa v181, v179 dst_sel:BYTE_3 dst_unused:UNUSED_PRESERVE src0_sel:DWORD
	global_store_dwordx2 v[196:197], v[180:181], off
	v_pk_mul_f32 v[182:183], v[70:71], s[20:21] op_sel:[0,1] op_sel_hi:[1,1]
	v_pk_mul_f32 v[184:185], v[72:73], s[20:21] op_sel:[0,1] op_sel_hi:[1,1]
	v_pk_mul_f32 v[186:187], v[66:67], s[20:21] op_sel:[0,1] op_sel_hi:[1,1]
	v_pk_mul_f32 v[188:189], v[68:69], s[20:21] op_sel:[0,1] op_sel_hi:[1,1]
	v_exp_f32_e32 v182, v182
	v_exp_f32_e32 v183, v183
	v_exp_f32_e32 v184, v184
	v_exp_f32_e32 v185, v185
	v_exp_f32_e32 v186, v186
	v_exp_f32_e32 v187, v187
	v_exp_f32_e32 v188, v188
	v_exp_f32_e32 v189, v189
	v_pk_add_f32 v[182:183], v[182:183], 1.0 op_sel_hi:[1,0]
	v_pk_add_f32 v[184:185], v[184:185], 1.0 op_sel_hi:[1,0]
	v_pk_add_f32 v[186:187], v[186:187], 1.0 op_sel_hi:[1,0]
	v_pk_add_f32 v[188:189], v[188:189], 1.0 op_sel_hi:[1,0]
	v_rcp_f32_e32 v182, v182
	v_rcp_f32_e32 v183, v183
	v_rcp_f32_e32 v184, v184
	v_rcp_f32_e32 v185, v185
	v_rcp_f32_e32 v186, v186
	v_rcp_f32_e32 v187, v187
	v_rcp_f32_e32 v188, v188
	v_rcp_f32_e32 v189, v189
	s_nop 0
	v_pk_fma_f32 v[182:183], v[182:183], s[20:21], 0.5 op_sel_hi:[1,0,0]
	v_pk_fma_f32 v[184:185], v[184:185], s[20:21], 0.5 op_sel_hi:[1,0,0]
	v_pk_fma_f32 v[186:187], v[186:187], s[20:21], 0.5 op_sel_hi:[1,0,0]
	v_pk_fma_f32 v[188:189], v[188:189], s[20:21], 0.5 op_sel_hi:[1,0,0]
	v_cvt_u32_f32_e32 v190, v182
	v_cvt_u32_f32_e32 v191, v186
	v_cvt_u32_f32_sdwa v190, v183 dst_sel:BYTE_1 dst_unused:UNUSED_PRESERVE src0_sel:DWORD
	v_cvt_u32_f32_sdwa v191, v187 dst_sel:BYTE_1 dst_unused:UNUSED_PRESERVE src0_sel:DWORD
	v_cvt_u32_f32_sdwa v190, v184 dst_sel:BYTE_2 dst_unused:UNUSED_PRESERVE src0_sel:DWORD
	v_cvt_u32_f32_sdwa v191, v188 dst_sel:BYTE_2 dst_unused:UNUSED_PRESERVE src0_sel:DWORD
	v_cvt_u32_f32_sdwa v190, v185 dst_sel:BYTE_3 dst_unused:UNUSED_PRESERVE src0_sel:DWORD
	v_cvt_u32_f32_sdwa v191, v189 dst_sel:BYTE_3 dst_unused:UNUSED_PRESERVE src0_sel:DWORD
	global_store_dwordx2 v[196:197], v[190:191], off offset:128
	v_pk_mul_f32 v[172:173], v[62:63], s[20:21] op_sel:[0,1] op_sel_hi:[1,1]
	v_pk_mul_f32 v[174:175], v[64:65], s[20:21] op_sel:[0,1] op_sel_hi:[1,1]
	v_pk_mul_f32 v[176:177], v[58:59], s[20:21] op_sel:[0,1] op_sel_hi:[1,1]
	v_pk_mul_f32 v[178:179], v[60:61], s[20:21] op_sel:[0,1] op_sel_hi:[1,1]
	v_exp_f32_e32 v172, v172
	v_exp_f32_e32 v173, v173
	v_exp_f32_e32 v174, v174
	v_exp_f32_e32 v175, v175
	v_exp_f32_e32 v176, v176
	v_exp_f32_e32 v177, v177
	v_exp_f32_e32 v178, v178
	v_exp_f32_e32 v179, v179
	v_pk_add_f32 v[172:173], v[172:173], 1.0 op_sel_hi:[1,0]
	v_pk_add_f32 v[174:175], v[174:175], 1.0 op_sel_hi:[1,0]
	v_pk_add_f32 v[176:177], v[176:177], 1.0 op_sel_hi:[1,0]
	v_pk_add_f32 v[178:179], v[178:179], 1.0 op_sel_hi:[1,0]
	v_rcp_f32_e32 v172, v172
	v_rcp_f32_e32 v173, v173
	v_rcp_f32_e32 v174, v174
	v_rcp_f32_e32 v175, v175
	v_rcp_f32_e32 v176, v176
	v_rcp_f32_e32 v177, v177
	v_rcp_f32_e32 v178, v178
	v_rcp_f32_e32 v179, v179
	s_mov_b64 s[0:1], 0x80000
	v_lshl_add_u64 v[194:195], v[192:193], 0, s[0:1]
; __device__ __forceinline__ float sigmoidf_(float x) { return __builtin_amdgcn_rcpf(1.f + __expf(-x)); }
;     __device__ __forceinline__ void operator()(f32x4 (&acc)[2][2][4][2], const pg8::Unit& u, int wr, int wc, int fr, int fq) const {
;     ...
;             for (int ai = 0; ai < 2; ++ai)
; #pragma unroll
;                 for (int m = 0; m < 4; ++m) {
;                     unsigned char* gp = gq + (size_t)(row0 + ai * 128 + m * 16) * 4096 + (u.pn - 28) * 256 + cin;
; #pragma unroll
;                     for (int bj = 0; bj < 2; ++bj) { unsigned w2[2];
; #pragma unroll
;                         for (int n = 0; n < 2; ++n) {
;                             const f32x4 v = acc[ai][bj][m][n];
;                             const unsigned b0 = (unsigned)(sigmoidf_(v[0]) * 255.f + 0.5f), b1 = (unsigned)(sigmoidf_(v[1]) * 255.f + 0.5f),
;                                            b2 = (unsigned)(sigmoidf_(v[2]) * 255.f + 0.5f), b3 = (unsigned)(sigmoidf_(v[3]) * 255.f + 0.5f);
;                             w2[n] = b0 | (b1 << 8) | (b2 << 16) | (b3 << 24);
;                         }
;                         u32x2 o = {w2[0], w2[1]}; *(u32x2*)(gp + bj * 128) = o; }
	v_pk_fma_f32 v[172:173], v[172:173], s[20:21], 0.5 op_sel_hi:[1,0,0]
	v_pk_fma_f32 v[174:175], v[174:175], s[20:21], 0.5 op_sel_hi:[1,0,0]
	v_pk_fma_f32 v[176:177], v[176:177], s[20:21], 0.5 op_sel_hi:[1,0,0]
	v_pk_fma_f32 v[178:179], v[178:179], s[20:21], 0.5 op_sel_hi:[1,0,0]
	v_cvt_u32_f32_e32 v180, v172
	v_cvt_u32_f32_e32 v181, v176
	v_cvt_u32_f32_sdwa v180, v173 dst_sel:BYTE_1 dst_unused:UNUSED_PRESERVE src0_sel:DWORD
	v_cvt_u32_f32_sdwa v181, v177 dst_sel:BYTE_1 dst_unused:UNUSED_PRESERVE src0_sel:DWORD
	v_cvt_u32_f32_sdwa v180, v174 dst_sel:BYTE_2 dst_unused:UNUSED_PRESERVE src0_sel:DWORD
	v_cvt_u32_f32_sdwa v181, v178 dst_sel:BYTE_2 dst_unused:UNUSED_PRESERVE src0_sel:DWORD
	v_cvt_u32_f32_sdwa v180, v175 dst_sel:BYTE_3 dst_unused:UNUSED_PRESERVE src0_sel:DWORD
	v_cvt_u32_f32_sdwa v181, v179 dst_sel:BYTE_3 dst_unused:UNUSED_PRESERVE src0_sel:DWORD
	global_store_dwordx2 v[194:195], v[180:181], off
	v_pk_mul_f32 v[182:183], v[54:55], s[20:21] op_sel:[0,1] op_sel_hi:[1,1]
	v_pk_mul_f32 v[184:185], v[56:57], s[20:21] op_sel:[0,1] op_sel_hi:[1,1]
	v_pk_mul_f32 v[186:187], v[46:47], s[20:21] op_sel:[0,1] op_sel_hi:[1,1]
	v_pk_mul_f32 v[188:189], v[48:49], s[20:21] op_sel:[0,1] op_sel_hi:[1,1]
	v_exp_f32_e32 v182, v182
	v_exp_f32_e32 v183, v183
	v_exp_f32_e32 v184, v184
	v_exp_f32_e32 v185, v185
	v_exp_f32_e32 v186, v186
	v_exp_f32_e32 v187, v187
	v_exp_f32_e32 v188, v188
	v_exp_f32_e32 v189, v189
	v_pk_add_f32 v[182:183], v[182:183], 1.0 op_sel_hi:[1,0]
	v_pk_add_f32 v[184:185], v[184:185], 1.0 op_sel_hi:[1,0]
	v_pk_add_f32 v[186:187], v[186:187], 1.0 op_sel_hi:[1,0]
	v_pk_add_f32 v[188:189], v[188:189], 1.0 op_sel_hi:[1,0]
	v_rcp_f32_e32 v182, v182
	v_rcp_f32_e32 v183, v183
	v_rcp_f32_e32 v184, v184
	v_rcp_f32_e32 v185, v185
	v_rcp_f32_e32 v186, v186
	v_rcp_f32_e32 v187, v187
	v_rcp_f32_e32 v188, v188
	v_rcp_f32_e32 v189, v189
	s_nop 0
	v_pk_fma_f32 v[182:183], v[182:183], s[20:21], 0.5 op_sel_hi:[1,0,0]
	v_pk_fma_f32 v[184:185], v[184:185], s[20:21], 0.5 op_sel_hi:[1,0,0]
	v_pk_fma_f32 v[186:187], v[186:187], s[20:21], 0.5 op_sel_hi:[1,0,0]
	v_pk_fma_f32 v[188:189], v[188:189], s[20:21], 0.5 op_sel_hi:[1,0,0]
	v_cvt_u32_f32_e32 v190, v182
	v_cvt_u32_f32_e32 v191, v186
	v_cvt_u32_f32_sdwa v190, v183 dst_sel:BYTE_1 dst_unused:UNUSED_PRESERVE src0_sel:DWORD
	v_cvt_u32_f32_sdwa v191, v187 dst_sel:BYTE_1 dst_unused:UNUSED_PRESERVE src0_sel:DWORD
	v_cvt_u32_f32_sdwa v190, v184 dst_sel:BYTE_2 dst_unused:UNUSED_PRESERVE src0_sel:DWORD
	v_cvt_u32_f32_sdwa v191, v188 dst_sel:BYTE_2 dst_unused:UNUSED_PRESERVE src0_sel:DWORD
	v_cvt_u32_f32_sdwa v190, v185 dst_sel:BYTE_3 dst_unused:UNUSED_PRESERVE src0_sel:DWORD
	v_cvt_u32_f32_sdwa v191, v189 dst_sel:BYTE_3 dst_unused:UNUSED_PRESERVE src0_sel:DWORD
	global_store_dwordx2 v[194:195], v[190:191], off offset:128
	v_pk_mul_f32 v[172:173], v[50:51], s[20:21] op_sel:[0,1] op_sel_hi:[1,1]
	v_pk_mul_f32 v[174:175], v[52:53], s[20:21] op_sel:[0,1] op_sel_hi:[1,1]
	v_pk_mul_f32 v[176:177], v[42:43], s[20:21] op_sel:[0,1] op_sel_hi:[1,1]
	v_pk_mul_f32 v[178:179], v[44:45], s[20:21] op_sel:[0,1] op_sel_hi:[1,1]
	v_exp_f32_e32 v172, v172
	v_exp_f32_e32 v173, v173
	v_exp_f32_e32 v174, v174
	v_exp_f32_e32 v175, v175
	v_exp_f32_e32 v176, v176
	v_exp_f32_e32 v177, v177
	v_exp_f32_e32 v178, v178
	v_exp_f32_e32 v179, v179
	v_pk_add_f32 v[172:173], v[172:173], 1.0 op_sel_hi:[1,0]
	v_pk_add_f32 v[174:175], v[174:175], 1.0 op_sel_hi:[1,0]
	v_pk_add_f32 v[176:177], v[176:177], 1.0 op_sel_hi:[1,0]
	v_pk_add_f32 v[178:179], v[178:179], 1.0 op_sel_hi:[1,0]
	v_rcp_f32_e32 v172, v172
	v_rcp_f32_e32 v173, v173
	v_rcp_f32_e32 v174, v174
	v_rcp_f32_e32 v175, v175
	v_rcp_f32_e32 v176, v176
	v_rcp_f32_e32 v177, v177
	v_rcp_f32_e32 v178, v178
	v_rcp_f32_e32 v179, v179
	s_mov_b64 s[0:1], 0x90000
	v_lshl_add_u64 v[196:197], v[192:193], 0, s[0:1]
	v_pk_fma_f32 v[172:173], v[172:173], s[20:21], 0.5 op_sel_hi:[1,0,0]
	v_pk_fma_f32 v[174:175], v[174:175], s[20:21], 0.5 op_sel_hi:[1,0,0]
	v_pk_fma_f32 v[176:177], v[176:177], s[20:21], 0.5 op_sel_hi:[1,0,0]
	v_pk_fma_f32 v[178:179], v[178:179], s[20:21], 0.5 op_sel_hi:[1,0,0]
	v_cvt_u32_f32_e32 v180, v172
	v_cvt_u32_f32_e32 v181, v176
	v_cvt_u32_f32_sdwa v180, v173 dst_sel:BYTE_1 dst_unused:UNUSED_PRESERVE src0_sel:DWORD
	v_cvt_u32_f32_sdwa v181, v177 dst_sel:BYTE_1 dst_unused:UNUSED_PRESERVE src0_sel:DWORD
	v_cvt_u32_f32_sdwa v180, v174 dst_sel:BYTE_2 dst_unused:UNUSED_PRESERVE src0_sel:DWORD
	v_cvt_u32_f32_sdwa v181, v178 dst_sel:BYTE_2 dst_unused:UNUSED_PRESERVE src0_sel:DWORD
	v_cvt_u32_f32_sdwa v180, v175 dst_sel:BYTE_3 dst_unused:UNUSED_PRESERVE src0_sel:DWORD
	v_cvt_u32_f32_sdwa v181, v179 dst_sel:BYTE_3 dst_unused:UNUSED_PRESERVE src0_sel:DWORD
	global_store_dwordx2 v[196:197], v[180:181], off
	v_pk_mul_f32 v[182:183], v[34:35], s[20:21] op_sel:[0,1] op_sel_hi:[1,1]
	v_pk_mul_f32 v[184:185], v[36:37], s[20:21] op_sel:[0,1] op_sel_hi:[1,1]
	v_pk_mul_f32 v[186:187], v[26:27], s[20:21] op_sel:[0,1] op_sel_hi:[1,1]
	v_pk_mul_f32 v[188:189], v[28:29], s[20:21] op_sel:[0,1] op_sel_hi:[1,1]
	v_exp_f32_e32 v182, v182
	v_exp_f32_e32 v183, v183
	v_exp_f32_e32 v184, v184
	v_exp_f32_e32 v185, v185
	v_exp_f32_e32 v186, v186
	v_exp_f32_e32 v187, v187
	v_exp_f32_e32 v188, v188
	v_exp_f32_e32 v189, v189
	v_pk_add_f32 v[182:183], v[182:183], 1.0 op_sel_hi:[1,0]
	v_pk_add_f32 v[184:185], v[184:185], 1.0 op_sel_hi:[1,0]
	v_pk_add_f32 v[186:187], v[186:187], 1.0 op_sel_hi:[1,0]
	v_pk_add_f32 v[188:189], v[188:189], 1.0 op_sel_hi:[1,0]
	v_rcp_f32_e32 v182, v182
	v_rcp_f32_e32 v183, v183
	v_rcp_f32_e32 v184, v184
	v_rcp_f32_e32 v185, v185
	v_rcp_f32_e32 v186, v186
	v_rcp_f32_e32 v187, v187
; __device__ __forceinline__ float sigmoidf_(float x) { return __builtin_amdgcn_rcpf(1.f + __expf(-x)); }
;     __device__ __forceinline__ void operator()(f32x4 (&acc)[2][2][4][2], const pg8::Unit& u, int wr, int wc, int fr, int fq) const {
;     ...
;             for (int ai = 0; ai < 2; ++ai)
; #pragma unroll
;                 for (int m = 0; m < 4; ++m) {
;                     unsigned char* gp = gq + (size_t)(row0 + ai * 128 + m * 16) * 4096 + (u.pn - 28) * 256 + cin;
; #pragma unroll
;                     for (int bj = 0; bj < 2; ++bj) { unsigned w2[2];
; #pragma unroll
;                         for (int n = 0; n < 2; ++n) {
;                             const f32x4 v = acc[ai][bj][m][n];
;                             const unsigned b0 = (unsigned)(sigmoidf_(v[0]) * 255.f + 0.5f), b1 = (unsigned)(sigmoidf_(v[1]) * 255.f + 0.5f),
;                                            b2 = (unsigned)(sigmoidf_(v[2]) * 255.f + 0.5f), b3 = (unsigned)(sigmoidf_(v[3]) * 255.f + 0.5f);
;                             w2[n] = b0 | (b1 << 8) | (b2 << 16) | (b3 << 24);
;                         }
;                         u32x2 o = {w2[0], w2[1]}; *(u32x2*)(gp + bj * 128) = o; }
	v_rcp_f32_e32 v188, v188
	v_rcp_f32_e32 v189, v189
	s_nop 0
	v_pk_fma_f32 v[182:183], v[182:183], s[20:21], 0.5 op_sel_hi:[1,0,0]
	v_pk_fma_f32 v[184:185], v[184:185], s[20:21], 0.5 op_sel_hi:[1,0,0]
	v_pk_fma_f32 v[186:187], v[186:187], s[20:21], 0.5 op_sel_hi:[1,0,0]
	v_pk_fma_f32 v[188:189], v[188:189], s[20:21], 0.5 op_sel_hi:[1,0,0]
	v_cvt_u32_f32_e32 v190, v182
	v_cvt_u32_f32_e32 v191, v186
	v_cvt_u32_f32_sdwa v190, v183 dst_sel:BYTE_1 dst_unused:UNUSED_PRESERVE src0_sel:DWORD
	v_cvt_u32_f32_sdwa v191, v187 dst_sel:BYTE_1 dst_unused:UNUSED_PRESERVE src0_sel:DWORD
	v_cvt_u32_f32_sdwa v190, v184 dst_sel:BYTE_2 dst_unused:UNUSED_PRESERVE src0_sel:DWORD
	v_cvt_u32_f32_sdwa v191, v188 dst_sel:BYTE_2 dst_unused:UNUSED_PRESERVE src0_sel:DWORD
	v_cvt_u32_f32_sdwa v190, v185 dst_sel:BYTE_3 dst_unused:UNUSED_PRESERVE src0_sel:DWORD
	v_cvt_u32_f32_sdwa v191, v189 dst_sel:BYTE_3 dst_unused:UNUSED_PRESERVE src0_sel:DWORD
	global_store_dwordx2 v[196:197], v[190:191], off offset:128
	v_pk_mul_f32 v[172:173], v[38:39], s[20:21] op_sel:[0,1] op_sel_hi:[1,1]
	v_pk_mul_f32 v[174:175], v[40:41], s[20:21] op_sel:[0,1] op_sel_hi:[1,1]
	v_pk_mul_f32 v[176:177], v[30:31], s[20:21] op_sel:[0,1] op_sel_hi:[1,1]
	v_pk_mul_f32 v[178:179], v[32:33], s[20:21] op_sel:[0,1] op_sel_hi:[1,1]
	v_exp_f32_e32 v172, v172
	v_exp_f32_e32 v173, v173
	v_exp_f32_e32 v174, v174
	v_exp_f32_e32 v175, v175
	v_exp_f32_e32 v176, v176
	v_exp_f32_e32 v177, v177
	v_exp_f32_e32 v178, v178
	v_exp_f32_e32 v179, v179
	v_pk_add_f32 v[172:173], v[172:173], 1.0 op_sel_hi:[1,0]
	v_pk_add_f32 v[174:175], v[174:175], 1.0 op_sel_hi:[1,0]
	v_pk_add_f32 v[176:177], v[176:177], 1.0 op_sel_hi:[1,0]
	v_pk_add_f32 v[178:179], v[178:179], 1.0 op_sel_hi:[1,0]
	v_rcp_f32_e32 v172, v172
	v_rcp_f32_e32 v173, v173
	v_rcp_f32_e32 v174, v174
	v_rcp_f32_e32 v175, v175
	v_rcp_f32_e32 v176, v176
	v_rcp_f32_e32 v177, v177
	v_rcp_f32_e32 v178, v178
	v_rcp_f32_e32 v179, v179
	s_mov_b64 s[0:1], 0xa0000
	v_lshl_add_u64 v[194:195], v[192:193], 0, s[0:1]
	v_pk_fma_f32 v[172:173], v[172:173], s[20:21], 0.5 op_sel_hi:[1,0,0]
	v_pk_fma_f32 v[174:175], v[174:175], s[20:21], 0.5 op_sel_hi:[1,0,0]
	v_pk_fma_f32 v[176:177], v[176:177], s[20:21], 0.5 op_sel_hi:[1,0,0]
	v_pk_fma_f32 v[178:179], v[178:179], s[20:21], 0.5 op_sel_hi:[1,0,0]
	v_cvt_u32_f32_e32 v180, v172
	v_cvt_u32_f32_e32 v181, v176
	v_cvt_u32_f32_sdwa v180, v173 dst_sel:BYTE_1 dst_unused:UNUSED_PRESERVE src0_sel:DWORD
	v_cvt_u32_f32_sdwa v181, v177 dst_sel:BYTE_1 dst_unused:UNUSED_PRESERVE src0_sel:DWORD
	v_cvt_u32_f32_sdwa v180, v174 dst_sel:BYTE_2 dst_unused:UNUSED_PRESERVE src0_sel:DWORD
	v_cvt_u32_f32_sdwa v181, v178 dst_sel:BYTE_2 dst_unused:UNUSED_PRESERVE src0_sel:DWORD
	v_cvt_u32_f32_sdwa v180, v175 dst_sel:BYTE_3 dst_unused:UNUSED_PRESERVE src0_sel:DWORD
	v_cvt_u32_f32_sdwa v181, v179 dst_sel:BYTE_3 dst_unused:UNUSED_PRESERVE src0_sel:DWORD
	global_store_dwordx2 v[194:195], v[180:181], off
	v_pk_mul_f32 v[182:183], v[18:19], s[20:21] op_sel:[0,1] op_sel_hi:[1,1]
	v_pk_mul_f32 v[184:185], v[20:21], s[20:21] op_sel:[0,1] op_sel_hi:[1,1]
	v_pk_mul_f32 v[186:187], v[10:11], s[20:21] op_sel:[0,1] op_sel_hi:[1,1]
	v_pk_mul_f32 v[188:189], v[12:13], s[20:21] op_sel:[0,1] op_sel_hi:[1,1]
	v_exp_f32_e32 v182, v182
	v_exp_f32_e32 v183, v183
	v_exp_f32_e32 v184, v184
	v_exp_f32_e32 v185, v185
	v_exp_f32_e32 v186, v186
	v_exp_f32_e32 v187, v187
	v_exp_f32_e32 v188, v188
	v_exp_f32_e32 v189, v189
	v_pk_add_f32 v[182:183], v[182:183], 1.0 op_sel_hi:[1,0]
	v_pk_add_f32 v[184:185], v[184:185], 1.0 op_sel_hi:[1,0]
	v_pk_add_f32 v[186:187], v[186:187], 1.0 op_sel_hi:[1,0]
	v_pk_add_f32 v[188:189], v[188:189], 1.0 op_sel_hi:[1,0]
	v_rcp_f32_e32 v182, v182
	v_rcp_f32_e32 v183, v183
	v_rcp_f32_e32 v184, v184
	v_rcp_f32_e32 v185, v185
	v_rcp_f32_e32 v186, v186
	v_rcp_f32_e32 v187, v187
	v_rcp_f32_e32 v188, v188
	v_rcp_f32_e32 v189, v189
	s_nop 0
	v_pk_fma_f32 v[182:183], v[182:183], s[20:21], 0.5 op_sel_hi:[1,0,0]
	v_pk_fma_f32 v[184:185], v[184:185], s[20:21], 0.5 op_sel_hi:[1,0,0]
	v_pk_fma_f32 v[186:187], v[186:187], s[20:21], 0.5 op_sel_hi:[1,0,0]
	v_pk_fma_f32 v[188:189], v[188:189], s[20:21], 0.5 op_sel_hi:[1,0,0]
	v_cvt_u32_f32_e32 v190, v182
	v_cvt_u32_f32_e32 v191, v186
	v_cvt_u32_f32_sdwa v190, v183 dst_sel:BYTE_1 dst_unused:UNUSED_PRESERVE src0_sel:DWORD
; __device__ __forceinline__ float sigmoidf_(float x) { return __builtin_amdgcn_rcpf(1.f + __expf(-x)); }
;     __device__ __forceinline__ void operator()(f32x4 (&acc)[2][2][4][2], const pg8::Unit& u, int wr, int wc, int fr, int fq) const {
;     ...
;             for (int ai = 0; ai < 2; ++ai)
; #pragma unroll
;                 for (int m = 0; m < 4; ++m) {
;                     unsigned char* gp = gq + (size_t)(row0 + ai * 128 + m * 16) * 4096 + (u.pn - 28) * 256 + cin;
; #pragma unroll
;                     for (int bj = 0; bj < 2; ++bj) { unsigned w2[2];
; #pragma unroll
;                         for (int n = 0; n < 2; ++n) {
;                             const f32x4 v = acc[ai][bj][m][n];
;                             const unsigned b0 = (unsigned)(sigmoidf_(v[0]) * 255.f + 0.5f), b1 = (unsigned)(sigmoidf_(v[1]) * 255.f + 0.5f),
;                                            b2 = (unsigned)(sigmoidf_(v[2]) * 255.f + 0.5f), b3 = (unsigned)(sigmoidf_(v[3]) * 255.f + 0.5f);
;                             w2[n] = b0 | (b1 << 8) | (b2 << 16) | (b3 << 24);
;                         }
;                         u32x2 o = {w2[0], w2[1]}; *(u32x2*)(gp + bj * 128) = o; }
	v_cvt_u32_f32_sdwa v191, v187 dst_sel:BYTE_1 dst_unused:UNUSED_PRESERVE src0_sel:DWORD
	v_cvt_u32_f32_sdwa v190, v184 dst_sel:BYTE_2 dst_unused:UNUSED_PRESERVE src0_sel:DWORD
	v_cvt_u32_f32_sdwa v191, v188 dst_sel:BYTE_2 dst_unused:UNUSED_PRESERVE src0_sel:DWORD
	v_cvt_u32_f32_sdwa v190, v185 dst_sel:BYTE_3 dst_unused:UNUSED_PRESERVE src0_sel:DWORD
	v_cvt_u32_f32_sdwa v191, v189 dst_sel:BYTE_3 dst_unused:UNUSED_PRESERVE src0_sel:DWORD
	global_store_dwordx2 v[194:195], v[190:191], off offset:128
	v_pk_mul_f32 v[172:173], v[22:23], s[20:21] op_sel:[0,1] op_sel_hi:[1,1]
	v_pk_mul_f32 v[174:175], v[24:25], s[20:21] op_sel:[0,1] op_sel_hi:[1,1]
	v_pk_mul_f32 v[176:177], v[14:15], s[20:21] op_sel:[0,1] op_sel_hi:[1,1]
	v_pk_mul_f32 v[178:179], v[16:17], s[20:21] op_sel:[0,1] op_sel_hi:[1,1]
	v_exp_f32_e32 v172, v172
	v_exp_f32_e32 v173, v173
	v_exp_f32_e32 v174, v174
	v_exp_f32_e32 v175, v175
	v_exp_f32_e32 v176, v176
	v_exp_f32_e32 v177, v177
	v_exp_f32_e32 v178, v178
	v_exp_f32_e32 v179, v179
	v_pk_add_f32 v[172:173], v[172:173], 1.0 op_sel_hi:[1,0]
	v_pk_add_f32 v[174:175], v[174:175], 1.0 op_sel_hi:[1,0]
	v_pk_add_f32 v[176:177], v[176:177], 1.0 op_sel_hi:[1,0]
	v_pk_add_f32 v[178:179], v[178:179], 1.0 op_sel_hi:[1,0]
	v_rcp_f32_e32 v172, v172
	v_rcp_f32_e32 v173, v173
	v_rcp_f32_e32 v174, v174
	v_rcp_f32_e32 v175, v175
	v_rcp_f32_e32 v176, v176
	v_rcp_f32_e32 v177, v177
	v_rcp_f32_e32 v178, v178
	v_rcp_f32_e32 v179, v179
	s_mov_b64 s[0:1], 0xb0000
	v_lshl_add_u64 v[196:197], v[192:193], 0, s[0:1]
	v_pk_fma_f32 v[172:173], v[172:173], s[20:21], 0.5 op_sel_hi:[1,0,0]
	v_pk_fma_f32 v[174:175], v[174:175], s[20:21], 0.5 op_sel_hi:[1,0,0]
	v_pk_fma_f32 v[176:177], v[176:177], s[20:21], 0.5 op_sel_hi:[1,0,0]
	v_pk_fma_f32 v[178:179], v[178:179], s[20:21], 0.5 op_sel_hi:[1,0,0]
	v_cvt_u32_f32_e32 v180, v172
	v_cvt_u32_f32_e32 v181, v176
	v_cvt_u32_f32_sdwa v180, v173 dst_sel:BYTE_1 dst_unused:UNUSED_PRESERVE src0_sel:DWORD
	v_cvt_u32_f32_sdwa v181, v177 dst_sel:BYTE_1 dst_unused:UNUSED_PRESERVE src0_sel:DWORD
	v_cvt_u32_f32_sdwa v180, v174 dst_sel:BYTE_2 dst_unused:UNUSED_PRESERVE src0_sel:DWORD
	v_cvt_u32_f32_sdwa v181, v178 dst_sel:BYTE_2 dst_unused:UNUSED_PRESERVE src0_sel:DWORD
	v_cvt_u32_f32_sdwa v180, v175 dst_sel:BYTE_3 dst_unused:UNUSED_PRESERVE src0_sel:DWORD
	v_cvt_u32_f32_sdwa v181, v179 dst_sel:BYTE_3 dst_unused:UNUSED_PRESERVE src0_sel:DWORD
	global_store_dwordx2 v[196:197], v[180:181], off
	v_pk_mul_f32 v[182:183], v[6:7], s[20:21] op_sel:[0,1] op_sel_hi:[1,1]
	v_pk_mul_f32 v[184:185], v[8:9], s[20:21] op_sel:[0,1] op_sel_hi:[1,1]
	v_pk_mul_f32 v[186:187], v[2:3], s[20:21] op_sel:[0,1] op_sel_hi:[1,1]
	v_pk_mul_f32 v[188:189], v[4:5], s[20:21] op_sel:[0,1] op_sel_hi:[1,1]
	v_exp_f32_e32 v182, v182
	v_exp_f32_e32 v183, v183
	v_exp_f32_e32 v184, v184
	v_exp_f32_e32 v185, v185
	v_exp_f32_e32 v186, v186
	v_exp_f32_e32 v187, v187
	v_exp_f32_e32 v188, v188
	v_exp_f32_e32 v189, v189
	v_pk_add_f32 v[182:183], v[182:183], 1.0 op_sel_hi:[1,0]
	v_pk_add_f32 v[184:185], v[184:185], 1.0 op_sel_hi:[1,0]
	v_pk_add_f32 v[186:187], v[186:187], 1.0 op_sel_hi:[1,0]
	v_pk_add_f32 v[188:189], v[188:189], 1.0 op_sel_hi:[1,0]
	v_rcp_f32_e32 v182, v182
	v_rcp_f32_e32 v183, v183
	v_rcp_f32_e32 v184, v184
	v_rcp_f32_e32 v185, v185
	v_rcp_f32_e32 v186, v186
	v_rcp_f32_e32 v187, v187
	v_rcp_f32_e32 v188, v188
	v_rcp_f32_e32 v189, v189
	s_nop 0
	v_pk_fma_f32 v[182:183], v[182:183], s[20:21], 0.5 op_sel_hi:[1,0,0]
	v_pk_fma_f32 v[184:185], v[184:185], s[20:21], 0.5 op_sel_hi:[1,0,0]
	v_pk_fma_f32 v[186:187], v[186:187], s[20:21], 0.5 op_sel_hi:[1,0,0]
	v_pk_fma_f32 v[188:189], v[188:189], s[20:21], 0.5 op_sel_hi:[1,0,0]
	v_cvt_u32_f32_e32 v190, v182
	v_cvt_u32_f32_e32 v191, v186
	v_cvt_u32_f32_sdwa v190, v183 dst_sel:BYTE_1 dst_unused:UNUSED_PRESERVE src0_sel:DWORD
	v_cvt_u32_f32_sdwa v191, v187 dst_sel:BYTE_1 dst_unused:UNUSED_PRESERVE src0_sel:DWORD
	v_cvt_u32_f32_sdwa v190, v184 dst_sel:BYTE_2 dst_unused:UNUSED_PRESERVE src0_sel:DWORD
	v_cvt_u32_f32_sdwa v191, v188 dst_sel:BYTE_2 dst_unused:UNUSED_PRESERVE src0_sel:DWORD
	v_cvt_u32_f32_sdwa v190, v185 dst_sel:BYTE_3 dst_unused:UNUSED_PRESERVE src0_sel:DWORD
	v_cvt_u32_f32_sdwa v191, v189 dst_sel:BYTE_3 dst_unused:UNUSED_PRESERVE src0_sel:DWORD
	global_store_dwordx2 v[196:197], v[190:191], off offset:128
